# K-loop heads aligned to 64 bytes (padding never executed); GATE GEMM unit order in incremental form
# baseline (speedup 1.0000x reference)
;     __device__ bool next(int i, Unit& u) const {
;         const long L = (long)i * G + c; if (L >= nwg) return false;
;         int wgid = (int)L; { const int q = nwg / NXCD, r = nwg % NXCD, xcd = wgid % NXCD, off = wgid / NXCD; wgid = (xcd < r ? xcd * (q + 1) : r * (q + 1) + (xcd - r) * q) + off; }
;         const int nig = wgm * nN, gid = wgid / nig, fm = gid * wgm, gsz = (nM - fm) < wgm ? (nM - fm) : wgm;
;         u.pm = fm + ((wgid % nig) % gsz); u.pn = (wgid % nig) / gsz; return true;
;     }
; template <class Epi>
; __device__ __forceinline__ void gemm_phase(LAS unsigned char* lds, const Gemm g, const StaticOrder& S, const Epi& E, const int tid) {
;     ...
;         const bool has_next = S.next(ui + 1, nxt);
.LBB0_173:
	s_add_i32 s55, s55, 1
	s_cmp_lt_u32 s55, 4
	s_cselect_b64 s[6:7], -1, 0
	s_cbranch_scc0 .LBB0_179
	s_add_i32 s56, s59, 4
	s_mov_b32 s57, s58
	s_cmp_lt_i32 s56, 8
	s_cbranch_scc1 .LBB0_179
	s_sub_i32 s56, s56, 8
	s_add_i32 s57, s58, 8

; #define PG8_STAGE(bufoff, gbase, voff) do { _Pragma("unroll") for (int _i = 0; _i < 2; ++_i) \
;         __builtin_amdgcn_global_load_lds((const unsigned*)((const char*)(gbase) + (voff)[_i]), (LAS unsigned*)(lds + (bufoff) + ldsw + _i * 8192), 16, 0, 0); } while (0)
; #define PG8_LDA(dst, b, h) do { _Pragma("unroll") for (int m = 0; m < 4; ++m) _Pragma("unroll") for (int k = 0; k < 2; ++k) dst[m][k] = *(const LAS bf16x8*)(lds + PG8_SA(b, h) + aoff + m * 2048 + k * 1024); } while (0)
; #define PG8_LDB(dst, b, h) do { _Pragma("unroll") for (int n = 0; n < 2; ++n) _Pragma("unroll") for (int k = 0; k < 2; ++k) dst[n][k] = *(const LAS bf16x8*)(lds + PG8_SB(b, h) + boff + n * 2048 + k * 1024); } while (0)
; #define PG8_MMA(ai, bj, At, Bt) do { __builtin_amdgcn_s_setprio(1); _Pragma("unroll") for (int m = 0; m < 4; ++m) _Pragma("unroll") for (int n = 0; n < 2; ++n) _Pragma("unroll") for (int k = 0; k < 2; ++k) \
;         acc[ai][bj][m][n] = __builtin_amdgcn_mfma_f32_16x16x32_bf16(Bt[n][k], At[m][k], acc[ai][bj][m][n], 0, 0, 0); __builtin_amdgcn_s_setprio(0); } while (0)
; #define PG8_WAIT_V(n) asm volatile("s_waitcnt vmcnt(" #n ")" ::: "memory")
; #define PG8_WAIT_L(n) asm volatile("s_waitcnt lgkmcnt(" #n ")" ::: "memory")
; #define PG8_BAR __builtin_amdgcn_s_barrier()
; #define PG8_SCHED __builtin_amdgcn_sched_barrier(0)
; template <class Epi>
; __device__ __forceinline__ void gemm_phase(LAS unsigned char* lds, const Gemm g, const StaticOrder& S, const Epi& E, const int tid) {
;     ...
;         for (int t = 0; t < nt; t += 2) {
;             const bool last = (t == nt - 2);
;             const char* a1 = cA + (size_t)(t + 1) * kstep;
;             const char* a2 = last ? nA : cA + (size_t)(t + 2) * kstep; const char* b2 = last ? nB : cB + (size_t)(t + 2) * kstep;
;             const char* a3 = a2 + kstep; const char* b3 = b2 + kstep;
;             PG8_LDB(B0, 0, 0); PG8_LDB(B1, 0, 1); PG8_SCHED; PG8_LDA(At, 0, 0); PG8_STAGE(PG8_SA(1, 1), a1 + hstepA, voffA);
;             PG8_WAIT_V(8); PG8_WAIT_L(0); PG8_BAR; PG8_MMA(0, 0, At, B0); PG8_MMA(0, 1, At, B1); PG8_BAR; PG8_SCHED;
;             PG8_LDA(At, 0, 1); PG8_STAGE(PG8_SB(0, 0), b2, voffB); PG8_STAGE(PG8_SB(0, 1), b2 + hstepB, voffB); PG8_STAGE(PG8_SA(0, 0), a2, voffA);
;             PG8_WAIT_V(8); PG8_WAIT_L(0); PG8_BAR; PG8_MMA(1, 0, At, B0); PG8_MMA(1, 1, At, B1); PG8_BAR; PG8_SCHED;
.LBB0_183:
	v_mov_b32_e32 v137, 0
	s_andn2_b64 vcc, exec, s[96:97]
	s_cbranch_vccnz .LBB0_187
	s_add_u32 s0, s36, 0x100
	s_addc_u32 s1, s37, 0
	s_add_u32 s6, s38, 0x80
	s_addc_u32 s7, s39, 0
	s_mov_b32 s36, 0
	s_add_i32 s38, s36, 2
	s_add_u32 s39, s6, 0x80
	s_addc_u32 s37, s7, 0
	s_add_i32 s62, 0, 0x10000
	s_cmp_eq_u32 s53, s36
	s_cselect_b32 s37, s31, s37
	s_cselect_b32 s36, s30, s39
	s_cselect_b32 s61, s35, s1
	s_cselect_b32 s60, s34, s0
	s_add_i32 s39, 0, 0x14000
	v_add_u32_e32 v152, s62, v168
	v_add_u32_e32 v170, s39, v168
	ds_read_b128 v[82:85], v152
	ds_read_b128 v[86:89], v152 offset:1024
	ds_read_b128 v[138:141], v152 offset:2048
	ds_read_b128 v[152:155], v152 offset:3072
	ds_read_b128 v[156:159], v170
	ds_read_b128 v[160:163], v170 offset:1024
	ds_read_b128 v[164:167], v170 offset:2048
	ds_read_b128 v[170:173], v170 offset:3072
	v_lshl_add_u64 v[194:195], s[6:7], 0, v[150:151]
	s_add_i32 m0, s44, 0xc000
	ds_read_b128 v[174:177], v169
	ds_read_b128 v[178:181], v169 offset:1024
	ds_read_b128 v[182:185], v169 offset:2048
	ds_read_b128 v[186:189], v169 offset:3072
	ds_read_b128 v[190:193], v169 offset:4096
	ds_read_b128 v[202:205], v169 offset:5120
	ds_read_b128 v[206:209], v169 offset:6144
	ds_read_b128 v[210:213], v169 offset:7168
	global_load_lds_dwordx4 v[194:195], off
	v_lshl_add_u64 v[194:195], s[6:7], 0, v[148:149]
	s_add_i32 m0, s44, 0xe000
	s_nop 0
	global_load_lds_dwordx4 v[194:195], off
	s_waitcnt vmcnt(8)
	s_waitcnt lgkmcnt(0)
	s_barrier
	s_setprio 1
	s_waitcnt lgkmcnt(0)
	v_mfma_f32_16x16x32_bf16 v[134:137], v[82:85], v[174:177], 0
	v_mfma_f32_16x16x32_bf16 v[62:65], v[138:141], v[174:177], 0
	v_mfma_f32_16x16x32_bf16 v[126:129], v[82:85], v[182:185], 0
	v_mfma_f32_16x16x32_bf16 v[54:57], v[138:141], v[182:185], 0
	v_mfma_f32_16x16x32_bf16 v[118:121], v[82:85], v[190:193], 0
	v_mfma_f32_16x16x32_bf16 v[46:49], v[138:141], v[190:193], 0
	v_mfma_f32_16x16x32_bf16 v[110:113], v[82:85], v[206:209], 0
	v_mfma_f32_16x16x32_bf16 v[38:41], v[138:141], v[206:209], 0
	v_mfma_f32_16x16x32_bf16 v[134:137], v[86:89], v[178:181], v[134:137]
	v_mfma_f32_16x16x32_bf16 v[62:65], v[152:155], v[178:181], v[62:65]
	v_mfma_f32_16x16x32_bf16 v[126:129], v[86:89], v[186:189], v[126:129]
	v_mfma_f32_16x16x32_bf16 v[54:57], v[152:155], v[186:189], v[54:57]
	v_mfma_f32_16x16x32_bf16 v[118:121], v[86:89], v[202:205], v[118:121]
	v_mfma_f32_16x16x32_bf16 v[46:49], v[152:155], v[202:205], v[46:49]
	v_mfma_f32_16x16x32_bf16 v[110:113], v[86:89], v[210:213], v[110:113]
	v_mfma_f32_16x16x32_bf16 v[38:41], v[152:155], v[210:213], v[38:41]
	s_setprio 0
	s_setprio 1
	v_mfma_f32_16x16x32_bf16 v[130:133], v[156:159], v[174:177], 0
	v_mfma_f32_16x16x32_bf16 v[58:61], v[164:167], v[174:177], 0
	v_mfma_f32_16x16x32_bf16 v[122:125], v[156:159], v[182:185], 0
	v_mfma_f32_16x16x32_bf16 v[50:53], v[164:167], v[182:185], 0
	v_mfma_f32_16x16x32_bf16 v[114:117], v[156:159], v[190:193], 0
	v_mfma_f32_16x16x32_bf16 v[42:45], v[164:167], v[190:193], 0
	v_mfma_f32_16x16x32_bf16 v[106:109], v[156:159], v[206:209], 0
	v_mfma_f32_16x16x32_bf16 v[34:37], v[164:167], v[206:209], 0
	v_mfma_f32_16x16x32_bf16 v[130:133], v[160:163], v[178:181], v[130:133]
	v_mfma_f32_16x16x32_bf16 v[58:61], v[170:173], v[178:181], v[58:61]
	v_mfma_f32_16x16x32_bf16 v[122:125], v[160:163], v[186:189], v[122:125]
	v_mfma_f32_16x16x32_bf16 v[50:53], v[170:173], v[186:189], v[50:53]
	v_mfma_f32_16x16x32_bf16 v[114:117], v[160:163], v[202:205], v[114:117]
	v_mfma_f32_16x16x32_bf16 v[42:45], v[170:173], v[202:205], v[42:45]
	v_mfma_f32_16x16x32_bf16 v[106:109], v[160:163], v[210:213], v[106:109]
	v_mfma_f32_16x16x32_bf16 v[34:37], v[170:173], v[210:213], v[34:37]
	s_setprio 0
	s_barrier
; #define PG8_STAGE(bufoff, gbase, voff) do { _Pragma("unroll") for (int _i = 0; _i < 2; ++_i) \
;         __builtin_amdgcn_global_load_lds((const unsigned*)((const char*)(gbase) + (voff)[_i]), (LAS unsigned*)(lds + (bufoff) + ldsw + _i * 8192), 16, 0, 0); } while (0)
; #define PG8_LDA(dst, b, h) do { _Pragma("unroll") for (int m = 0; m < 4; ++m) _Pragma("unroll") for (int k = 0; k < 2; ++k) dst[m][k] = *(const LAS bf16x8*)(lds + PG8_SA(b, h) + aoff + m * 2048 + k * 1024); } while (0)
; #define PG8_LDB(dst, b, h) do { _Pragma("unroll") for (int n = 0; n < 2; ++n) _Pragma("unroll") for (int k = 0; k < 2; ++k) dst[n][k] = *(const LAS bf16x8*)(lds + PG8_SB(b, h) + boff + n * 2048 + k * 1024); } while (0)
; #define PG8_MMA(ai, bj, At, Bt) do { __builtin_amdgcn_s_setprio(1); _Pragma("unroll") for (int m = 0; m < 4; ++m) _Pragma("unroll") for (int n = 0; n < 2; ++n) _Pragma("unroll") for (int k = 0; k < 2; ++k) \
;         acc[ai][bj][m][n] = __builtin_amdgcn_mfma_f32_16x16x32_bf16(Bt[n][k], At[m][k], acc[ai][bj][m][n], 0, 0, 0); __builtin_amdgcn_s_setprio(0); } while (0)
; #define PG8_WAIT_V(n) asm volatile("s_waitcnt vmcnt(" #n ")" ::: "memory")
; #define PG8_WAIT_L(n) asm volatile("s_waitcnt lgkmcnt(" #n ")" ::: "memory")
; #define PG8_BAR __builtin_amdgcn_s_barrier()
; #define PG8_SCHED __builtin_amdgcn_sched_barrier(0)
; template <class Epi>
; __device__ __forceinline__ void gemm_phase(LAS unsigned char* lds, const Gemm g, const StaticOrder& S, const Epi& E, const int tid) {
;     ...
;             PG8_LDA(At, 0, 1); PG8_STAGE(PG8_SB(0, 0), b2, voffB); PG8_STAGE(PG8_SB(0, 1), b2 + hstepB, voffB); PG8_STAGE(PG8_SA(0, 0), a2, voffA);
;             PG8_WAIT_V(8); PG8_WAIT_L(0); PG8_BAR; PG8_MMA(1, 0, At, B0); PG8_MMA(1, 1, At, B1); PG8_BAR; PG8_SCHED;
;             PG8_LDB(B0, 1, 0); PG8_LDB(B1, 1, 1); PG8_SCHED; PG8_LDA(At, 1, 0); PG8_STAGE(PG8_SA(0, 1), a2 + hstepA, voffA);
;             PG8_WAIT_V(8); PG8_WAIT_L(0); PG8_BAR; PG8_MMA(0, 0, At, B0); PG8_MMA(0, 1, At, B1); PG8_BAR; PG8_SCHED;
;             PG8_LDA(At, 1, 1); PG8_STAGE(PG8_SB(1, 0), b3, voffB); PG8_STAGE(PG8_SB(1, 1), b3 + hstepB, voffB); PG8_STAGE(PG8_SA(1, 0), a3, voffA);
;             PG8_WAIT_V(8); PG8_WAIT_L(0); PG8_BAR; PG8_MMA(1, 0, At, B0); PG8_MMA(1, 1, At, B1); PG8_BAR; PG8_SCHED;
	s_add_i32 s62, s62, s3
	v_lshl_add_u64 v[194:195], s[60:61], 0, v[0:1]
	s_mov_b32 m0, s62
	ds_read_b128 v[174:177], v169 offset:16384
	ds_read_b128 v[178:181], v169 offset:17408
	ds_read_b128 v[182:185], v169 offset:18432
	ds_read_b128 v[186:189], v169 offset:19456
	ds_read_b128 v[190:193], v169 offset:20480
	ds_read_b128 v[202:205], v169 offset:21504
	ds_read_b128 v[206:209], v169 offset:22528
	ds_read_b128 v[210:213], v169 offset:23552
	global_load_lds_dwordx4 v[194:195], off
	s_add_i32 m0, s62, 0x2000
	v_lshl_add_u64 v[196:197], s[60:61], 0, v[146:147]
	s_add_u32 s60, s60, s12
	s_addc_u32 s61, s61, s13
	s_add_i32 s39, s39, s3
	global_load_lds_dwordx4 v[196:197], off
	v_lshl_add_u64 v[198:199], s[60:61], 0, v[0:1]
	s_mov_b32 m0, s39
	v_lshl_add_u64 v[214:215], s[60:61], 0, v[146:147]
	global_load_lds_dwordx4 v[198:199], off
	s_add_i32 m0, s39, 0x2000
	v_lshl_add_u64 v[216:217], s[36:37], 0, v[142:143]
	global_load_lds_dwordx4 v[214:215], off
	s_mov_b32 m0, s44
	v_lshl_add_u64 v[218:219], s[36:37], 0, v[144:145]
	global_load_lds_dwordx4 v[216:217], off
	s_mov_b32 m0, s45
	s_nop 0
	global_load_lds_dwordx4 v[218:219], off
	s_waitcnt vmcnt(8)
	s_waitcnt lgkmcnt(0)
	s_barrier
	s_setprio 1
	s_waitcnt lgkmcnt(0)
	v_mfma_f32_16x16x32_bf16 v[102:105], v[82:85], v[174:177], 0
	v_mfma_f32_16x16x32_bf16 v[30:33], v[138:141], v[174:177], 0
	v_mfma_f32_16x16x32_bf16 v[94:97], v[82:85], v[182:185], 0
	v_mfma_f32_16x16x32_bf16 v[22:25], v[138:141], v[182:185], 0
	v_mfma_f32_16x16x32_bf16 v[78:81], v[82:85], v[190:193], 0
	v_mfma_f32_16x16x32_bf16 v[14:17], v[138:141], v[190:193], 0
	v_mfma_f32_16x16x32_bf16 v[70:73], v[82:85], v[206:209], 0
	v_mfma_f32_16x16x32_bf16 v[6:9], v[138:141], v[206:209], 0
	v_mfma_f32_16x16x32_bf16 v[102:105], v[86:89], v[178:181], v[102:105]
	v_mfma_f32_16x16x32_bf16 v[30:33], v[152:155], v[178:181], v[30:33]
	v_mfma_f32_16x16x32_bf16 v[94:97], v[86:89], v[186:189], v[94:97]
	v_mfma_f32_16x16x32_bf16 v[22:25], v[152:155], v[186:189], v[22:25]
	v_mfma_f32_16x16x32_bf16 v[78:81], v[86:89], v[202:205], v[78:81]
	v_mfma_f32_16x16x32_bf16 v[14:17], v[152:155], v[202:205], v[14:17]
	v_mfma_f32_16x16x32_bf16 v[70:73], v[86:89], v[210:213], v[70:73]
	v_mfma_f32_16x16x32_bf16 v[6:9], v[152:155], v[210:213], v[6:9]
	s_setprio 0
	s_setprio 1
	v_mfma_f32_16x16x32_bf16 v[26:29], v[164:167], v[174:177], 0
	v_mfma_f32_16x16x32_bf16 v[18:21], v[164:167], v[182:185], 0
	v_mfma_f32_16x16x32_bf16 v[74:77], v[156:159], v[190:193], 0
	v_mfma_f32_16x16x32_bf16 v[10:13], v[164:167], v[190:193], 0
	v_mfma_f32_16x16x32_bf16 v[66:69], v[156:159], v[206:209], 0
	v_mfma_f32_16x16x32_bf16 v[2:5], v[164:167], v[206:209], 0
	v_mfma_f32_16x16x32_bf16 v[82:85], v[156:159], v[174:177], 0
	v_mfma_f32_16x16x32_bf16 v[26:29], v[170:173], v[178:181], v[26:29]
	v_mfma_f32_16x16x32_bf16 v[86:89], v[156:159], v[182:185], 0
	v_mfma_f32_16x16x32_bf16 v[18:21], v[170:173], v[186:189], v[18:21]
	v_mfma_f32_16x16x32_bf16 v[74:77], v[160:163], v[202:205], v[74:77]
	v_mfma_f32_16x16x32_bf16 v[10:13], v[170:173], v[202:205], v[10:13]
	v_mfma_f32_16x16x32_bf16 v[66:69], v[160:163], v[210:213], v[66:69]
	v_mfma_f32_16x16x32_bf16 v[2:5], v[170:173], v[210:213], v[2:5]
	v_mfma_f32_16x16x32_bf16 v[82:85], v[160:163], v[178:181], v[82:85]
	v_mfma_f32_16x16x32_bf16 v[86:89], v[160:163], v[186:189], v[86:89]
	s_setprio 0
	s_barrier
	s_branch .Lkl185_sp2
	.p2alignl 6, 3212836864

; #define PG8_STAGE(bufoff, gbase, voff) do { _Pragma("unroll") for (int _i = 0; _i < 2; ++_i) \
;         __builtin_amdgcn_global_load_lds((const unsigned*)((const char*)(gbase) + (voff)[_i]), (LAS unsigned*)(lds + (bufoff) + ldsw + _i * 8192), 16, 0, 0); } while (0)
; #define PG8_LDA(dst, b, h) do { _Pragma("unroll") for (int m = 0; m < 4; ++m) _Pragma("unroll") for (int k = 0; k < 2; ++k) dst[m][k] = *(const LAS bf16x8*)(lds + PG8_SA(b, h) + aoff + m * 2048 + k * 1024); } while (0)
; #define PG8_MMA(ai, bj, At, Bt) do { __builtin_amdgcn_s_setprio(1); _Pragma("unroll") for (int m = 0; m < 4; ++m) _Pragma("unroll") for (int n = 0; n < 2; ++n) _Pragma("unroll") for (int k = 0; k < 2; ++k) \
;         acc[ai][bj][m][n] = __builtin_amdgcn_mfma_f32_16x16x32_bf16(Bt[n][k], At[m][k], acc[ai][bj][m][n], 0, 0, 0); __builtin_amdgcn_s_setprio(0); } while (0)
; #define PG8_WAIT_V(n) asm volatile("s_waitcnt vmcnt(" #n ")" ::: "memory")
; #define PG8_WAIT_L(n) asm volatile("s_waitcnt lgkmcnt(" #n ")" ::: "memory")
; #define PG8_BAR __builtin_amdgcn_s_barrier()
; #define PG8_SCHED __builtin_amdgcn_sched_barrier(0)
; template <class Epi>
; __device__ __forceinline__ void gemm_phase(LAS unsigned char* lds, const Gemm g, const StaticOrder& S, const Epi& E, const int tid) {
;     ...
;             PG8_WAIT_V(8); PG8_WAIT_L(0); PG8_BAR; PG8_MMA(0, 0, At, B0); PG8_MMA(0, 1, At, B1); PG8_BAR; PG8_SCHED;
;             PG8_LDA(At, 1, 1); PG8_STAGE(PG8_SB(1, 0), b3, voffB); PG8_STAGE(PG8_SB(1, 1), b3 + hstepB, voffB); PG8_STAGE(PG8_SA(1, 0), a3, voffA);
;             PG8_WAIT_V(8); PG8_WAIT_L(0); PG8_BAR; PG8_MMA(1, 0, At, B0); PG8_MMA(1, 1, At, B1); PG8_BAR; PG8_SCHED;
;         }
.Lkl298_w2j:
	s_waitcnt lgkmcnt(0)
	s_barrier
	s_setprio 1
	s_waitcnt lgkmcnt(0)
	v_mfma_f32_16x16x32_bf16 v[122:125], v[130:133], v[162:165], v[122:125]
	v_mfma_f32_16x16x32_bf16 v[126:129], v[138:141], v[162:165], v[126:129]
	v_mfma_f32_16x16x32_bf16 v[110:113], v[130:133], v[170:173], v[110:113]
	v_mfma_f32_16x16x32_bf16 v[106:109], v[138:141], v[170:173], v[106:109]
	v_mfma_f32_16x16x32_bf16 v[94:97], v[130:133], v[178:181], v[94:97]
	v_mfma_f32_16x16x32_bf16 v[90:93], v[138:141], v[178:181], v[90:93]
	v_mfma_f32_16x16x32_bf16 v[78:81], v[130:133], v[186:189], v[78:81]
	v_mfma_f32_16x16x32_bf16 v[74:77], v[138:141], v[186:189], v[74:77]
	v_mfma_f32_16x16x32_bf16 v[122:125], v[134:137], v[166:169], v[122:125]
	v_mfma_f32_16x16x32_bf16 v[126:129], v[142:145], v[166:169], v[126:129]
	v_mfma_f32_16x16x32_bf16 v[110:113], v[134:137], v[174:177], v[110:113]
	v_mfma_f32_16x16x32_bf16 v[106:109], v[142:145], v[174:177], v[106:109]
	v_mfma_f32_16x16x32_bf16 v[94:97], v[134:137], v[182:185], v[94:97]
	v_mfma_f32_16x16x32_bf16 v[90:93], v[142:145], v[182:185], v[90:93]
	v_mfma_f32_16x16x32_bf16 v[78:81], v[134:137], v[190:193], v[78:81]
	v_mfma_f32_16x16x32_bf16 v[74:77], v[142:145], v[190:193], v[74:77]
	s_setprio 0
	s_setprio 1
	v_mfma_f32_16x16x32_bf16 v[118:121], v[146:149], v[162:165], v[118:121]
	v_mfma_f32_16x16x32_bf16 v[114:117], v[154:157], v[162:165], v[114:117]
	v_mfma_f32_16x16x32_bf16 v[102:105], v[146:149], v[170:173], v[102:105]
	v_mfma_f32_16x16x32_bf16 v[98:101], v[154:157], v[170:173], v[98:101]
	v_mfma_f32_16x16x32_bf16 v[86:89], v[146:149], v[178:181], v[86:89]
	v_mfma_f32_16x16x32_bf16 v[82:85], v[154:157], v[178:181], v[82:85]
	v_mfma_f32_16x16x32_bf16 v[70:73], v[146:149], v[186:189], v[70:73]
	v_mfma_f32_16x16x32_bf16 v[66:69], v[154:157], v[186:189], v[66:69]
	v_mfma_f32_16x16x32_bf16 v[118:121], v[150:153], v[166:169], v[118:121]
	v_mfma_f32_16x16x32_bf16 v[114:117], v[158:161], v[166:169], v[114:117]
	v_mfma_f32_16x16x32_bf16 v[102:105], v[150:153], v[174:177], v[102:105]
	v_mfma_f32_16x16x32_bf16 v[98:101], v[158:161], v[174:177], v[98:101]
	v_mfma_f32_16x16x32_bf16 v[86:89], v[150:153], v[182:185], v[86:89]
	v_mfma_f32_16x16x32_bf16 v[82:85], v[158:161], v[182:185], v[82:85]
	v_mfma_f32_16x16x32_bf16 v[70:73], v[150:153], v[190:193], v[70:73]
	v_mfma_f32_16x16x32_bf16 v[66:69], v[158:161], v[190:193], v[66:69]
	s_setprio 0
	s_barrier
	s_branch .Lkl298_sp3
	.p2alignl 6, 3212836864

; #define PG8_STAGE(bufoff, gbase, voff) do { _Pragma("unroll") for (int _i = 0; _i < 2; ++_i) \
;         __builtin_amdgcn_global_load_lds((const unsigned*)((const char*)(gbase) + (voff)[_i]), (LAS unsigned*)(lds + (bufoff) + ldsw + _i * 8192), 16, 0, 0); } while (0)
; #define PG8_LDA(dst, b, h) do { _Pragma("unroll") for (int m = 0; m < 4; ++m) _Pragma("unroll") for (int k = 0; k < 2; ++k) dst[m][k] = *(const LAS bf16x8*)(lds + PG8_SA(b, h) + aoff + m * 2048 + k * 1024); } while (0)
; #define PG8_LDB(dst, b, h) do { _Pragma("unroll") for (int n = 0; n < 2; ++n) _Pragma("unroll") for (int k = 0; k < 2; ++k) dst[n][k] = *(const LAS bf16x8*)(lds + PG8_SB(b, h) + boff + n * 2048 + k * 1024); } while (0)
; #define PG8_MMA(ai, bj, At, Bt) do { __builtin_amdgcn_s_setprio(1); _Pragma("unroll") for (int m = 0; m < 4; ++m) _Pragma("unroll") for (int n = 0; n < 2; ++n) _Pragma("unroll") for (int k = 0; k < 2; ++k) \
;         acc[ai][bj][m][n] = __builtin_amdgcn_mfma_f32_16x16x32_bf16(Bt[n][k], At[m][k], acc[ai][bj][m][n], 0, 0, 0); __builtin_amdgcn_s_setprio(0); } while (0)
; #define PG8_WAIT_V(n) asm volatile("s_waitcnt vmcnt(" #n ")" ::: "memory")
; #define PG8_WAIT_L(n) asm volatile("s_waitcnt lgkmcnt(" #n ")" ::: "memory")
; #define PG8_BAR __builtin_amdgcn_s_barrier()
; #define PG8_SCHED __builtin_amdgcn_sched_barrier(0)
; template <class Epi>
; __device__ __forceinline__ void gemm_phase(LAS unsigned char* lds, const Gemm g, const StaticOrder& S, const Epi& E, const int tid) {
;     ...
;         for (int t = 0; t < nt; t += 2) {
;             const bool last = (t == nt - 2);
;             const char* a1 = cA + (size_t)(t + 1) * kstep;
;             const char* a2 = last ? nA : cA + (size_t)(t + 2) * kstep; const char* b2 = last ? nB : cB + (size_t)(t + 2) * kstep;
;             const char* a3 = a2 + kstep; const char* b3 = b2 + kstep;
;             PG8_LDB(B0, 0, 0); PG8_LDB(B1, 0, 1); PG8_SCHED; PG8_LDA(At, 0, 0); PG8_STAGE(PG8_SA(1, 1), a1 + hstepA, voffA);
;             PG8_WAIT_V(8); PG8_WAIT_L(0); PG8_BAR; PG8_MMA(0, 0, At, B0); PG8_MMA(0, 1, At, B1); PG8_BAR; PG8_SCHED;
;             PG8_LDA(At, 0, 1); PG8_STAGE(PG8_SB(0, 0), b2, voffB); PG8_STAGE(PG8_SB(0, 1), b2 + hstepB, voffB); PG8_STAGE(PG8_SA(0, 0), a2, voffA);
;             PG8_WAIT_V(8); PG8_WAIT_L(0); PG8_BAR; PG8_MMA(1, 0, At, B0); PG8_MMA(1, 1, At, B1); PG8_BAR; PG8_SCHED;
.LBB0_346:
	v_mov_b32_e32 v125, 0
	s_andn2_b64 vcc, exec, s[10:11]
	s_cbranch_vccnz .LBB0_349
	s_add_u32 s0, s36, 0x100
	s_addc_u32 s1, s37, 0
	s_add_u32 s36, s38, 0x80
	s_addc_u32 s37, s39, 0
	s_mov_b32 s38, 0
	s_add_i32 s62, s38, 2
	s_add_u32 s63, s36, 0x80
	s_addc_u32 s39, s37, 0
	s_add_i32 s66, 0, 0x10000
	s_cmp_eq_u32 s56, s38
	s_cselect_b32 s39, s7, s39
	s_cselect_b32 s38, s6, s63
	s_cselect_b32 s65, s31, s1
	s_cselect_b32 s64, s30, s0
	s_add_i32 s63, 0, 0x14000
	v_add_u32_e32 v142, s66, v234
	v_add_u32_e32 v158, s63, v234
	ds_read_b128 v[130:133], v142
	ds_read_b128 v[134:137], v142 offset:1024
	ds_read_b128 v[138:141], v142 offset:2048
	ds_read_b128 v[142:145], v142 offset:3072
	ds_read_b128 v[146:149], v158
	ds_read_b128 v[150:153], v158 offset:1024
	ds_read_b128 v[154:157], v158 offset:2048
	ds_read_b128 v[158:161], v158 offset:3072
	v_lshl_add_u64 v[194:195], s[36:37], 0, v[210:211]
	s_add_i32 m0, s44, 0xc000
	ds_read_b128 v[162:165], v235
	ds_read_b128 v[166:169], v235 offset:1024
	ds_read_b128 v[170:173], v235 offset:2048
	ds_read_b128 v[174:177], v235 offset:3072
	ds_read_b128 v[178:181], v235 offset:4096
	ds_read_b128 v[182:185], v235 offset:5120
	ds_read_b128 v[186:189], v235 offset:6144
	ds_read_b128 v[190:193], v235 offset:7168
	global_load_lds_dwordx4 v[194:195], off
	v_lshl_add_u64 v[194:195], s[36:37], 0, v[208:209]
	s_add_i32 m0, s44, 0xe000
	s_nop 0
	global_load_lds_dwordx4 v[194:195], off
	s_waitcnt vmcnt(8)
	s_waitcnt lgkmcnt(0)
	s_barrier
	s_setprio 1
	s_waitcnt lgkmcnt(0)
	v_mfma_f32_16x16x32_bf16 v[122:125], v[130:133], v[162:165], 0
	v_mfma_f32_16x16x32_bf16 v[126:129], v[138:141], v[162:165], 0
	v_mfma_f32_16x16x32_bf16 v[110:113], v[130:133], v[170:173], 0
	v_mfma_f32_16x16x32_bf16 v[106:109], v[138:141], v[170:173], 0
	v_mfma_f32_16x16x32_bf16 v[94:97], v[130:133], v[178:181], 0
	v_mfma_f32_16x16x32_bf16 v[90:93], v[138:141], v[178:181], 0
	v_mfma_f32_16x16x32_bf16 v[78:81], v[130:133], v[186:189], 0
	v_mfma_f32_16x16x32_bf16 v[74:77], v[138:141], v[186:189], 0
	v_mfma_f32_16x16x32_bf16 v[122:125], v[134:137], v[166:169], v[122:125]
	v_mfma_f32_16x16x32_bf16 v[126:129], v[142:145], v[166:169], v[126:129]
	v_mfma_f32_16x16x32_bf16 v[110:113], v[134:137], v[174:177], v[110:113]
	v_mfma_f32_16x16x32_bf16 v[106:109], v[142:145], v[174:177], v[106:109]
	v_mfma_f32_16x16x32_bf16 v[94:97], v[134:137], v[182:185], v[94:97]
	v_mfma_f32_16x16x32_bf16 v[90:93], v[142:145], v[182:185], v[90:93]
	v_mfma_f32_16x16x32_bf16 v[78:81], v[134:137], v[190:193], v[78:81]
	v_mfma_f32_16x16x32_bf16 v[74:77], v[142:145], v[190:193], v[74:77]
	s_setprio 0
	s_setprio 1
	v_mfma_f32_16x16x32_bf16 v[118:121], v[146:149], v[162:165], 0
	v_mfma_f32_16x16x32_bf16 v[114:117], v[154:157], v[162:165], 0
	v_mfma_f32_16x16x32_bf16 v[102:105], v[146:149], v[170:173], 0
	v_mfma_f32_16x16x32_bf16 v[98:101], v[154:157], v[170:173], 0
	v_mfma_f32_16x16x32_bf16 v[86:89], v[146:149], v[178:181], 0
	v_mfma_f32_16x16x32_bf16 v[82:85], v[154:157], v[178:181], 0
	v_mfma_f32_16x16x32_bf16 v[70:73], v[146:149], v[186:189], 0
	v_mfma_f32_16x16x32_bf16 v[66:69], v[154:157], v[186:189], 0
	v_mfma_f32_16x16x32_bf16 v[118:121], v[150:153], v[166:169], v[118:121]
	v_mfma_f32_16x16x32_bf16 v[114:117], v[158:161], v[166:169], v[114:117]
	v_mfma_f32_16x16x32_bf16 v[102:105], v[150:153], v[174:177], v[102:105]
	v_mfma_f32_16x16x32_bf16 v[98:101], v[158:161], v[174:177], v[98:101]
	v_mfma_f32_16x16x32_bf16 v[86:89], v[150:153], v[182:185], v[86:89]
	v_mfma_f32_16x16x32_bf16 v[82:85], v[158:161], v[182:185], v[82:85]
	v_mfma_f32_16x16x32_bf16 v[70:73], v[150:153], v[190:193], v[70:73]
	v_mfma_f32_16x16x32_bf16 v[66:69], v[158:161], v[190:193], v[66:69]
	s_setprio 0
	s_barrier
; #define PG8_STAGE(bufoff, gbase, voff) do { _Pragma("unroll") for (int _i = 0; _i < 2; ++_i) \
;         __builtin_amdgcn_global_load_lds((const unsigned*)((const char*)(gbase) + (voff)[_i]), (LAS unsigned*)(lds + (bufoff) + ldsw + _i * 8192), 16, 0, 0); } while (0)
; #define PG8_LDA(dst, b, h) do { _Pragma("unroll") for (int m = 0; m < 4; ++m) _Pragma("unroll") for (int k = 0; k < 2; ++k) dst[m][k] = *(const LAS bf16x8*)(lds + PG8_SA(b, h) + aoff + m * 2048 + k * 1024); } while (0)
; #define PG8_LDB(dst, b, h) do { _Pragma("unroll") for (int n = 0; n < 2; ++n) _Pragma("unroll") for (int k = 0; k < 2; ++k) dst[n][k] = *(const LAS bf16x8*)(lds + PG8_SB(b, h) + boff + n * 2048 + k * 1024); } while (0)
; #define PG8_MMA(ai, bj, At, Bt) do { __builtin_amdgcn_s_setprio(1); _Pragma("unroll") for (int m = 0; m < 4; ++m) _Pragma("unroll") for (int n = 0; n < 2; ++n) _Pragma("unroll") for (int k = 0; k < 2; ++k) \
;         acc[ai][bj][m][n] = __builtin_amdgcn_mfma_f32_16x16x32_bf16(Bt[n][k], At[m][k], acc[ai][bj][m][n], 0, 0, 0); __builtin_amdgcn_s_setprio(0); } while (0)
; #define PG8_WAIT_V(n) asm volatile("s_waitcnt vmcnt(" #n ")" ::: "memory")
; #define PG8_WAIT_L(n) asm volatile("s_waitcnt lgkmcnt(" #n ")" ::: "memory")
; #define PG8_BAR __builtin_amdgcn_s_barrier()
; #define PG8_SCHED __builtin_amdgcn_sched_barrier(0)
; template <class Epi>
; __device__ __forceinline__ void gemm_phase(LAS unsigned char* lds, const Gemm g, const StaticOrder& S, const Epi& E, const int tid) {
;     ...
;             PG8_LDA(At, 0, 1); PG8_STAGE(PG8_SB(0, 0), b2, voffB); PG8_STAGE(PG8_SB(0, 1), b2 + hstepB, voffB); PG8_STAGE(PG8_SA(0, 0), a2, voffA);
;             PG8_WAIT_V(8); PG8_WAIT_L(0); PG8_BAR; PG8_MMA(1, 0, At, B0); PG8_MMA(1, 1, At, B1); PG8_BAR; PG8_SCHED;
;             PG8_LDB(B0, 1, 0); PG8_LDB(B1, 1, 1); PG8_SCHED; PG8_LDA(At, 1, 0); PG8_STAGE(PG8_SA(0, 1), a2 + hstepA, voffA);
;             PG8_WAIT_V(8); PG8_WAIT_L(0); PG8_BAR; PG8_MMA(0, 0, At, B0); PG8_MMA(0, 1, At, B1); PG8_BAR; PG8_SCHED;
;             PG8_LDA(At, 1, 1); PG8_STAGE(PG8_SB(1, 0), b3, voffB); PG8_STAGE(PG8_SB(1, 1), b3 + hstepB, voffB); PG8_STAGE(PG8_SA(1, 0), a3, voffA);
;             PG8_WAIT_V(8); PG8_WAIT_L(0); PG8_BAR; PG8_MMA(1, 0, At, B0); PG8_MMA(1, 1, At, B1); PG8_BAR; PG8_SCHED;
	s_add_i32 s66, s66, s43
	v_lshl_add_u64 v[194:195], s[64:65], 0, v[0:1]
	s_mov_b32 m0, s66
	ds_read_b128 v[162:165], v235 offset:16384
	ds_read_b128 v[166:169], v235 offset:17408
	ds_read_b128 v[170:173], v235 offset:18432
	ds_read_b128 v[174:177], v235 offset:19456
	ds_read_b128 v[178:181], v235 offset:20480
	ds_read_b128 v[182:185], v235 offset:21504
	ds_read_b128 v[186:189], v235 offset:22528
	ds_read_b128 v[190:193], v235 offset:23552
	global_load_lds_dwordx4 v[194:195], off
	s_add_i32 m0, s66, 0x2000
	v_lshl_add_u64 v[212:213], s[64:65], 0, v[206:207]
	s_add_u32 s64, s64, s14
	s_addc_u32 s65, s65, s15
	s_add_i32 s63, s63, s43
	global_load_lds_dwordx4 v[212:213], off
	v_lshl_add_u64 v[214:215], s[64:65], 0, v[0:1]
	s_mov_b32 m0, s63
	v_lshl_add_u64 v[216:217], s[64:65], 0, v[206:207]
	global_load_lds_dwordx4 v[214:215], off
	s_add_i32 m0, s63, 0x2000
	v_lshl_add_u64 v[218:219], s[38:39], 0, v[202:203]
	global_load_lds_dwordx4 v[216:217], off
	s_mov_b32 m0, s44
	v_lshl_add_u64 v[220:221], s[38:39], 0, v[204:205]
	global_load_lds_dwordx4 v[218:219], off
	s_mov_b32 m0, s45
	s_nop 0
	global_load_lds_dwordx4 v[220:221], off
	s_waitcnt vmcnt(8)
	s_waitcnt lgkmcnt(0)
	s_barrier
	s_setprio 1
	s_waitcnt lgkmcnt(0)
	v_mfma_f32_16x16x32_bf16 v[62:65], v[130:133], v[162:165], 0
	v_mfma_f32_16x16x32_bf16 v[58:61], v[138:141], v[162:165], 0
	v_mfma_f32_16x16x32_bf16 v[46:49], v[130:133], v[170:173], 0
	v_mfma_f32_16x16x32_bf16 v[42:45], v[138:141], v[170:173], 0
	v_mfma_f32_16x16x32_bf16 v[30:33], v[130:133], v[178:181], 0
	v_mfma_f32_16x16x32_bf16 v[26:29], v[138:141], v[178:181], 0
	v_mfma_f32_16x16x32_bf16 v[14:17], v[130:133], v[186:189], 0
	v_mfma_f32_16x16x32_bf16 v[10:13], v[138:141], v[186:189], 0
	v_mfma_f32_16x16x32_bf16 v[62:65], v[134:137], v[166:169], v[62:65]
	v_mfma_f32_16x16x32_bf16 v[58:61], v[142:145], v[166:169], v[58:61]
	v_mfma_f32_16x16x32_bf16 v[46:49], v[134:137], v[174:177], v[46:49]
	v_mfma_f32_16x16x32_bf16 v[42:45], v[142:145], v[174:177], v[42:45]
	v_mfma_f32_16x16x32_bf16 v[30:33], v[134:137], v[182:185], v[30:33]
	v_mfma_f32_16x16x32_bf16 v[26:29], v[142:145], v[182:185], v[26:29]
	v_mfma_f32_16x16x32_bf16 v[14:17], v[134:137], v[190:193], v[14:17]
	v_mfma_f32_16x16x32_bf16 v[10:13], v[142:145], v[190:193], v[10:13]
	s_setprio 0
	s_setprio 1
	v_mfma_f32_16x16x32_bf16 v[54:57], v[146:149], v[162:165], 0
	v_mfma_f32_16x16x32_bf16 v[50:53], v[154:157], v[162:165], 0
	v_mfma_f32_16x16x32_bf16 v[38:41], v[146:149], v[170:173], 0
	v_mfma_f32_16x16x32_bf16 v[34:37], v[154:157], v[170:173], 0
	v_mfma_f32_16x16x32_bf16 v[22:25], v[146:149], v[178:181], 0
	v_mfma_f32_16x16x32_bf16 v[18:21], v[154:157], v[178:181], 0
	v_mfma_f32_16x16x32_bf16 v[6:9], v[146:149], v[186:189], 0
	v_mfma_f32_16x16x32_bf16 v[2:5], v[154:157], v[186:189], 0
	v_mfma_f32_16x16x32_bf16 v[54:57], v[150:153], v[166:169], v[54:57]
	v_mfma_f32_16x16x32_bf16 v[50:53], v[158:161], v[166:169], v[50:53]
	v_mfma_f32_16x16x32_bf16 v[38:41], v[150:153], v[174:177], v[38:41]
	v_mfma_f32_16x16x32_bf16 v[34:37], v[158:161], v[174:177], v[34:37]
	v_mfma_f32_16x16x32_bf16 v[22:25], v[150:153], v[182:185], v[22:25]
	v_mfma_f32_16x16x32_bf16 v[18:21], v[158:161], v[182:185], v[18:21]
	v_mfma_f32_16x16x32_bf16 v[6:9], v[150:153], v[190:193], v[6:9]
	v_mfma_f32_16x16x32_bf16 v[2:5], v[158:161], v[190:193], v[2:5]
	s_setprio 0
	s_barrier
	s_branch .Lkl348_sp2
	.p2alignl 6, 3212836864

; #define PG8_STAGE(bufoff, gbase, voff) do { _Pragma("unroll") for (int _i = 0; _i < 2; ++_i) \
;         __builtin_amdgcn_global_load_lds((const unsigned*)((const char*)(gbase) + (voff)[_i]), (LAS unsigned*)(lds + (bufoff) + ldsw + _i * 8192), 16, 0, 0); } while (0)
; #define PG8_LDA(dst, b, h) do { _Pragma("unroll") for (int m = 0; m < 4; ++m) _Pragma("unroll") for (int k = 0; k < 2; ++k) dst[m][k] = *(const LAS bf16x8*)(lds + PG8_SA(b, h) + aoff + m * 2048 + k * 1024); } while (0)
; #define PG8_MMA(ai, bj, At, Bt) do { __builtin_amdgcn_s_setprio(1); _Pragma("unroll") for (int m = 0; m < 4; ++m) _Pragma("unroll") for (int n = 0; n < 2; ++n) _Pragma("unroll") for (int k = 0; k < 2; ++k) \
;         acc[ai][bj][m][n] = __builtin_amdgcn_mfma_f32_16x16x32_bf16(Bt[n][k], At[m][k], acc[ai][bj][m][n], 0, 0, 0); __builtin_amdgcn_s_setprio(0); } while (0)
; #define PG8_WAIT_V(n) asm volatile("s_waitcnt vmcnt(" #n ")" ::: "memory")
; #define PG8_WAIT_L(n) asm volatile("s_waitcnt lgkmcnt(" #n ")" ::: "memory")
; #define PG8_BAR __builtin_amdgcn_s_barrier()
; #define PG8_SCHED __builtin_amdgcn_sched_barrier(0)
; template <class Epi>
; __device__ __forceinline__ void gemm_phase(LAS unsigned char* lds, const Gemm g, const StaticOrder& S, const Epi& E, const int tid) {
;     ...
;             PG8_WAIT_V(8); PG8_WAIT_L(0); PG8_BAR; PG8_MMA(0, 0, At, B0); PG8_MMA(0, 1, At, B1); PG8_BAR; PG8_SCHED;
;             PG8_LDA(At, 1, 1); PG8_STAGE(PG8_SB(1, 0), b3, voffB); PG8_STAGE(PG8_SB(1, 1), b3 + hstepB, voffB); PG8_STAGE(PG8_SA(1, 0), a3, voffA);
;             PG8_WAIT_V(8); PG8_WAIT_L(0); PG8_BAR; PG8_MMA(1, 0, At, B0); PG8_MMA(1, 1, At, B1); PG8_BAR; PG8_SCHED;
;         }
.Lkl427_w2j:
	s_waitcnt lgkmcnt(0)
	s_barrier
	s_setprio 1
	s_waitcnt lgkmcnt(0)
	v_mfma_f32_16x16x32_bf16 v[142:145], v[66:69], v[172:175], v[142:145]
	v_mfma_f32_16x16x32_bf16 v[138:141], v[74:77], v[172:175], v[138:141]
	v_mfma_f32_16x16x32_bf16 v[126:129], v[66:69], v[180:183], v[126:129]
	v_mfma_f32_16x16x32_bf16 v[122:125], v[74:77], v[180:183], v[122:125]
	v_mfma_f32_16x16x32_bf16 v[110:113], v[66:69], v[188:191], v[110:113]
	v_mfma_f32_16x16x32_bf16 v[106:109], v[74:77], v[188:191], v[106:109]
	v_mfma_f32_16x16x32_bf16 v[94:97], v[66:69], v[202:205], v[94:97]
	v_mfma_f32_16x16x32_bf16 v[90:93], v[74:77], v[202:205], v[90:93]
	v_mfma_f32_16x16x32_bf16 v[142:145], v[70:73], v[176:179], v[142:145]
	v_mfma_f32_16x16x32_bf16 v[138:141], v[78:81], v[176:179], v[138:141]
	v_mfma_f32_16x16x32_bf16 v[126:129], v[70:73], v[184:187], v[126:129]
	v_mfma_f32_16x16x32_bf16 v[122:125], v[78:81], v[184:187], v[122:125]
	v_mfma_f32_16x16x32_bf16 v[110:113], v[70:73], v[192:195], v[110:113]
	v_mfma_f32_16x16x32_bf16 v[106:109], v[78:81], v[192:195], v[106:109]
	v_mfma_f32_16x16x32_bf16 v[94:97], v[70:73], v[206:209], v[94:97]
	v_mfma_f32_16x16x32_bf16 v[90:93], v[78:81], v[206:209], v[90:93]
	s_setprio 0
	s_setprio 1
	v_mfma_f32_16x16x32_bf16 v[134:137], v[156:159], v[172:175], v[134:137]
	v_mfma_f32_16x16x32_bf16 v[130:133], v[164:167], v[172:175], v[130:133]
	v_mfma_f32_16x16x32_bf16 v[118:121], v[156:159], v[180:183], v[118:121]
	v_mfma_f32_16x16x32_bf16 v[114:117], v[164:167], v[180:183], v[114:117]
	v_mfma_f32_16x16x32_bf16 v[102:105], v[156:159], v[188:191], v[102:105]
	v_mfma_f32_16x16x32_bf16 v[98:101], v[164:167], v[188:191], v[98:101]
	v_mfma_f32_16x16x32_bf16 v[86:89], v[156:159], v[202:205], v[86:89]
	v_mfma_f32_16x16x32_bf16 v[82:85], v[164:167], v[202:205], v[82:85]
	v_mfma_f32_16x16x32_bf16 v[134:137], v[160:163], v[176:179], v[134:137]
	v_mfma_f32_16x16x32_bf16 v[130:133], v[168:171], v[176:179], v[130:133]
	v_mfma_f32_16x16x32_bf16 v[118:121], v[160:163], v[184:187], v[118:121]
	v_mfma_f32_16x16x32_bf16 v[114:117], v[168:171], v[184:187], v[114:117]
	v_mfma_f32_16x16x32_bf16 v[102:105], v[160:163], v[192:195], v[102:105]
	v_mfma_f32_16x16x32_bf16 v[98:101], v[168:171], v[192:195], v[98:101]
	v_mfma_f32_16x16x32_bf16 v[86:89], v[160:163], v[206:209], v[86:89]
	v_mfma_f32_16x16x32_bf16 v[82:85], v[168:171], v[206:209], v[82:85]
	s_setprio 0
	s_barrier
	s_branch .Lkl427_sp3
	.p2alignl 6, 3212836864

; #define PG8_STAGE(bufoff, gbase, voff) do { _Pragma("unroll") for (int _i = 0; _i < 2; ++_i) \
;         __builtin_amdgcn_global_load_lds((const unsigned*)((const char*)(gbase) + (voff)[_i]), (LAS unsigned*)(lds + (bufoff) + ldsw + _i * 8192), 16, 0, 0); } while (0)
; #define PG8_LDA(dst, b, h) do { _Pragma("unroll") for (int m = 0; m < 4; ++m) _Pragma("unroll") for (int k = 0; k < 2; ++k) dst[m][k] = *(const LAS bf16x8*)(lds + PG8_SA(b, h) + aoff + m * 2048 + k * 1024); } while (0)
; #define PG8_MMA(ai, bj, At, Bt) do { __builtin_amdgcn_s_setprio(1); _Pragma("unroll") for (int m = 0; m < 4; ++m) _Pragma("unroll") for (int n = 0; n < 2; ++n) _Pragma("unroll") for (int k = 0; k < 2; ++k) \
;         acc[ai][bj][m][n] = __builtin_amdgcn_mfma_f32_16x16x32_bf16(Bt[n][k], At[m][k], acc[ai][bj][m][n], 0, 0, 0); __builtin_amdgcn_s_setprio(0); } while (0)
; #define PG8_WAIT_V(n) asm volatile("s_waitcnt vmcnt(" #n ")" ::: "memory")
; #define PG8_WAIT_L(n) asm volatile("s_waitcnt lgkmcnt(" #n ")" ::: "memory")
; #define PG8_BAR __builtin_amdgcn_s_barrier()
; #define PG8_SCHED __builtin_amdgcn_sched_barrier(0)
; template <class Epi>
; __device__ __forceinline__ void gemm_phase(LAS unsigned char* lds, const Gemm g, const StaticOrder& S, const Epi& E, const int tid) {
;     ...
;             PG8_WAIT_V(8); PG8_WAIT_L(0); PG8_BAR; PG8_MMA(0, 0, At, B0); PG8_MMA(0, 1, At, B1); PG8_BAR; PG8_SCHED;
;             PG8_LDA(At, 1, 1); PG8_STAGE(PG8_SB(1, 0), b3, voffB); PG8_STAGE(PG8_SB(1, 1), b3 + hstepB, voffB); PG8_STAGE(PG8_SA(1, 0), a3, voffA);
;             PG8_WAIT_V(8); PG8_WAIT_L(0); PG8_BAR; PG8_MMA(1, 0, At, B0); PG8_MMA(1, 1, At, B1); PG8_BAR; PG8_SCHED;
;         }
.Lkl652_w2j:
	s_waitcnt lgkmcnt(0)
	s_barrier
	s_setprio 1
	s_waitcnt lgkmcnt(0)
	v_mfma_f32_16x16x32_bf16 v[110:113], v[130:133], v[162:165], v[110:113]
	v_mfma_f32_16x16x32_bf16 v[106:109], v[138:141], v[162:165], v[106:109]
	v_mfma_f32_16x16x32_bf16 v[94:97], v[130:133], v[170:173], v[94:97]
	v_mfma_f32_16x16x32_bf16 v[90:93], v[138:141], v[170:173], v[90:93]
	v_mfma_f32_16x16x32_bf16 v[114:117], v[130:133], v[192:195], v[114:117]
	v_mfma_f32_16x16x32_bf16 v[62:65], v[138:141], v[192:195], v[62:65]
	v_mfma_f32_16x16x32_bf16 v[126:129], v[130:133], v[210:213], v[126:129]
	v_mfma_f32_16x16x32_bf16 v[70:73], v[138:141], v[210:213], v[70:73]
	v_mfma_f32_16x16x32_bf16 v[110:113], v[134:137], v[166:169], v[110:113]
	v_mfma_f32_16x16x32_bf16 v[106:109], v[142:145], v[166:169], v[106:109]
	v_mfma_f32_16x16x32_bf16 v[94:97], v[134:137], v[174:177], v[94:97]
	v_mfma_f32_16x16x32_bf16 v[90:93], v[142:145], v[174:177], v[90:93]
	v_mfma_f32_16x16x32_bf16 v[114:117], v[134:137], v[206:209], v[114:117]
	v_mfma_f32_16x16x32_bf16 v[62:65], v[142:145], v[206:209], v[62:65]
	v_mfma_f32_16x16x32_bf16 v[126:129], v[134:137], v[214:217], v[126:129]
	v_mfma_f32_16x16x32_bf16 v[70:73], v[142:145], v[214:217], v[70:73]
	s_setprio 0
	s_setprio 1
	v_mfma_f32_16x16x32_bf16 v[102:105], v[146:149], v[162:165], v[102:105]
	v_mfma_f32_16x16x32_bf16 v[98:101], v[154:157], v[162:165], v[98:101]
	v_mfma_f32_16x16x32_bf16 v[86:89], v[146:149], v[170:173], v[86:89]
	v_mfma_f32_16x16x32_bf16 v[82:85], v[154:157], v[170:173], v[82:85]
	v_mfma_f32_16x16x32_bf16 v[118:121], v[146:149], v[192:195], v[118:121]
	v_mfma_f32_16x16x32_bf16 v[58:61], v[154:157], v[192:195], v[58:61]
	v_mfma_f32_16x16x32_bf16 v[122:125], v[146:149], v[210:213], v[122:125]
	v_mfma_f32_16x16x32_bf16 v[66:69], v[154:157], v[210:213], v[66:69]
	v_mfma_f32_16x16x32_bf16 v[102:105], v[150:153], v[166:169], v[102:105]
	v_mfma_f32_16x16x32_bf16 v[98:101], v[158:161], v[166:169], v[98:101]
	v_mfma_f32_16x16x32_bf16 v[86:89], v[150:153], v[174:177], v[86:89]
	v_mfma_f32_16x16x32_bf16 v[82:85], v[158:161], v[174:177], v[82:85]
	v_mfma_f32_16x16x32_bf16 v[118:121], v[150:153], v[206:209], v[118:121]
	v_mfma_f32_16x16x32_bf16 v[58:61], v[158:161], v[206:209], v[58:61]
	v_mfma_f32_16x16x32_bf16 v[122:125], v[150:153], v[214:217], v[122:125]
	v_mfma_f32_16x16x32_bf16 v[66:69], v[158:161], v[214:217], v[66:69]
	s_setprio 0
	s_barrier
	s_branch .Lkl652_sp3
	.p2alignl 6, 3212836864
